# dilated attention: defer bias-table wait to the staging point and drop vmcnt(0) before QK MFMAs so next-unit K/V prefetch overlaps compute
# baseline (speedup 1.0000x reference)
; __device__ __forceinline__ void attn_band64(const bf16_t* Ks, const bf16_t* Vt, const bf16x8 (&qf)[2], int a, int w, int quad, int fr,
;                                             const float* biasT, int kmin, f32x4 (&oacc)[4], float& mx_out, float& den_out) {
;     f32x4 s[10];
; #pragma unroll
;     for (int i = 0; i < 10; ++i) {
;         const int nt = (w + i) > 15 ? 15 : (w + i);
;         s[i] = (f32x4){0.f, 0.f, 0.f, 0.f};
; #pragma unroll
;         for (int ks = 0; ks < 2; ++ks) {
;             const bf16x8 kf = *(const bf16x8*)(Ks + (16 * nt + fr) * 72 + quad * 8 + 32 * ks);
;             s[i] = __builtin_amdgcn_mfma_f32_16x16x32_bf16(kf, qf[ks], s[i], 0, 0, 0);
;         }
;     }
;     float mx = -3.0e38f;
;     const float* tb = biasT + (127 - a + 4 * quad + 16 * w);
; #pragma unroll
;     for (int i = 0; i < 10; ++i) {
;         const bool dead = (kmin != 0) && ((w + i) < 8);
; #pragma unroll
;         for (int j = 0; j < 4; ++j) {
;             float v = s[i][j] * 0.18033688011112042f + tb[16 * i + j];
;             v = dead ? -1.0e30f : v;
; __device__ __forceinline__ void dil_stage(const DilRegs& R, unsigned char* buf, int tid) {
;     bf16_t* Ks = (bf16_t*)(buf + DA_KS); bf16_t* Vt = (bf16_t*)(buf + DA_VT); float* biasT = (float*)(buf + DA_BIAS);
; #pragma unroll
;     for (int i = 0; i < 4; ++i) { const int bi = 2 * (tid >> 3) + (i & 1) + 128 * (i >> 1), ch = tid & 7; *(u32x4*)(Ks + bi * 72 + ch * 8) = R.kv[i]; }
; #pragma unroll
;     for (int i = 0; i < 4; i += 2) { const int bi = 2 * (tid >> 3) + 128 * (i >> 1), ch = tid & 7; vt_store_pair(Vt, ch * 8, bi, R.vv[i], R.vv[i + 1]); }
;     if (tid < 383) biasT[tid] = R.bias;
; }
.LBB0_520:
	s_or_b64 exec, exec, s[2:3]
	s_movk_i32 s2, 0x48
	v_lshl_add_u32 v44, v60, 1, 0
	v_mul_lo_u32 v65, v58, s2
	v_lshl_add_u32 v45, v65, 1, v44
	v_mul_lo_u32 v66, v62, s2
	s_waitcnt vmcnt(3)
	ds_write_b128 v45, v[18:21]
	v_lshl_add_u32 v18, v66, 1, v44
	ds_write_b128 v18, v[26:29]
	ds_write_b128 v45, v[14:17] offset:18432
	ds_write_b128 v18, v[38:41] offset:18432
	v_mul_u32_u24_e32 v67, 0x216, v60
	v_lshlrev_b32_e32 v68, 1, v58
	s_waitcnt vmcnt(2)
	v_and_b32_e32 v15, 0xffff, v10
	v_and_b32_e32 v19, 0xffff, v30
	v_add3_u32 v14, v44, v67, v68
	v_lshl_or_b32 v15, v22, 16, v15
	v_lshl_or_b32 v19, v34, 16, v19
	v_lshrrev_b32_e32 v10, 16, v10
	ds_write2st64_b32 v14, v15, v19 offset0:144 offset1:145
	v_lshrrev_b32_e32 v15, 16, v30
	v_and_or_b32 v10, v22, s10, v10
	v_and_or_b32 v15, v34, s10, v15
	v_add_u32_e32 v19, 24, v14
	v_and_b32_e32 v16, 0xffff, v11
	ds_write2st64_b32 v19, v10, v15 offset0:146 offset1:147
	v_and_b32_e32 v10, 0xffff, v31
	v_lshl_or_b32 v16, v23, 16, v16
	v_lshl_or_b32 v10, v35, 16, v10
	v_add_u32_e32 v15, 48, v14
	v_lshrrev_b32_e32 v11, 16, v11
	ds_write2st64_b32 v15, v16, v10 offset0:148 offset1:149
	v_lshrrev_b32_e32 v10, 16, v31
	v_and_or_b32 v11, v23, s10, v11
	v_and_or_b32 v10, v35, s10, v10
	v_add_u32_e32 v15, 0x48, v14
	v_and_b32_e32 v17, 0xffff, v12
	ds_write2st64_b32 v15, v11, v10 offset0:150 offset1:151
	v_and_b32_e32 v10, 0xffff, v32
	v_lshl_or_b32 v17, v24, 16, v17
	v_lshl_or_b32 v10, v36, 16, v10
	v_add_u32_e32 v11, 0x60, v14
	v_lshrrev_b32_e32 v12, 16, v12
	ds_write2st64_b32 v11, v17, v10 offset0:152 offset1:153
	v_lshrrev_b32_e32 v10, 16, v32
	v_and_or_b32 v12, v24, s10, v12
	v_and_or_b32 v10, v36, s10, v10
	v_add_u32_e32 v11, 0x78, v14
	v_and_b32_e32 v18, 0xffff, v13
	ds_write2st64_b32 v11, v12, v10 offset0:154 offset1:155
	v_and_b32_e32 v10, 0xffff, v33
	v_lshl_or_b32 v18, v25, 16, v18
	v_lshl_or_b32 v10, v37, 16, v10
	v_add_u32_e32 v11, 0x90, v14
	v_lshrrev_b32_e32 v13, 16, v13
	ds_write2st64_b32 v11, v18, v10 offset0:156 offset1:157
	v_lshrrev_b32_e32 v10, 16, v33
	s_movk_i32 s2, 0x17f
	v_and_b32_e32 v42, 15, v51
	v_and_or_b32 v13, v25, s10, v13
	v_and_or_b32 v10, v37, s10, v10
	v_add_u32_e32 v11, 0xa8, v14
	v_cmp_gt_i32_e64 s[40:41], s2, v51
	ds_write2st64_b32 v11, v13, v10 offset0:158 offset1:159
	s_and_saveexec_b64 s[2:3], s[40:41]
	v_lshl_add_u32 v10, v51, 2, 0
	v_add_u32_e32 v10, 0x11600, v10
	ds_write_b32 v10, v43
	s_or_b64 exec, exec, s[2:3]
	v_ashrrev_i32_e32 v10, 6, v51
	v_min_i32_e32 v12, 15, v10
	v_lshl_or_b32 v12, v12, 4, v42
	s_movk_i32 s2, 0x90
	v_mul_lo_u32 v72, v12, s2
	v_min_i32_e32 v12, 14, v10
	v_lshlrev_b32_e32 v73, 4, v12
	v_or_b32_e32 v12, v73, v42
	v_mul_lo_u32 v12, v12, s2
	v_add_u32_e32 v74, 0x900, v12
	v_add_u32_e32 v12, 2, v10
	v_min_i32_e32 v13, 15, v12
	v_lshl_or_b32 v13, v13, 4, v42
	v_mul_lo_u32 v75, v13, s2
	v_min_i32_e32 v13, 12, v10
	v_lshl_or_b32 v13, v13, 4, v42
	v_mul_lo_u32 v13, v13, s2
	v_add_u32_e32 v76, 0x1b00, v13
	v_add_u32_e32 v13, 4, v10
	v_min_i32_e32 v14, 15, v13
	v_lshl_or_b32 v14, v14, 4, v42
	v_mul_lo_u32 v77, v14, s2
	v_min_i32_e32 v14, 10, v10
	v_lshl_or_b32 v14, v14, 4, v42
	v_mul_lo_u32 v14, v14, s2
	v_add_u32_e32 v78, 0x2d00, v14
	v_add_u32_e32 v14, 6, v10
	v_min_i32_e32 v15, 15, v14
	v_lshl_or_b32 v15, v15, 4, v42
	v_mul_lo_u32 v79, v15, s2
	v_min_i32_e32 v15, 8, v10
	v_lshl_or_b32 v15, v15, 4, v42
	v_mul_lo_u32 v15, v15, s2
	v_add_u32_e32 v80, 0x3f00, v15
	v_add_u32_e32 v15, 8, v10
	v_min_i32_e32 v16, 15, v15
	v_lshl_or_b32 v16, v16, 4, v42
	v_lshlrev_b32_e32 v69, 4, v10
	v_mul_lo_u32 v81, v16, s2
	v_min_i32_e32 v16, 6, v10
	v_cmp_gt_i32_e64 s[42:43], 8, v10
	v_cmp_gt_i32_e64 s[44:45], 7, v10
	v_cmp_gt_i32_e64 s[46:47], 6, v10
	v_cmp_gt_i32_e64 s[48:49], 5, v10
	v_cmp_gt_i32_e64 s[50:51], 4, v10
	v_cmp_gt_i32_e64 s[52:53], 3, v10
	v_cmp_gt_i32_e64 s[54:55], 2, v10
	v_cmp_gt_i32_e64 s[56:57], 1, v10
	v_cmp_gt_i32_e64 s[58:59], 0, v10
	v_cmp_gt_i32_e64 s[60:61], -1, v10
	v_min_i32_e32 v10, 14, v12
	v_lshl_or_b32 v16, v16, 4, v42
	v_lshlrev_b32_e32 v85, 4, v10
	v_min_i32_e32 v10, 14, v13
	v_mul_lo_u32 v16, v16, s2
	v_lshlrev_b32_e32 v87, 4, v10
	v_min_i32_e32 v10, 14, v14
	v_bfe_u32 v11, v51, 4, 2
	v_add_u32_e32 v82, 0x5100, v16
	v_xor_b32_e32 v16, 0x7f, v42
	v_lshlrev_b32_e32 v89, 4, v10
	v_min_i32_e32 v10, 14, v15
	v_or_b32_e32 v70, v69, v42
	v_lshlrev_b32_e32 v71, 4, v11
	v_lshlrev_b32_e32 v50, 2, v11
	s_mov_b32 s14, 0
	v_mul_u32_u24_e32 v83, 0x218, v42
	v_lshlrev_b32_e32 v84, 4, v12
	v_lshlrev_b32_e32 v86, 4, v13
	v_lshlrev_b32_e32 v88, 4, v14
	v_lshlrev_b32_e32 v90, 4, v15
	v_lshlrev_b32_e32 v91, 4, v10
	v_cmp_eq_u32_e64 s[62:63], 0, v11
	v_lshlrev_b32_e32 v92, 2, v16
	s_waitcnt lgkmcnt(0)
	s_barrier
	s_waitcnt vmcnt(0)
	s_branch .LBB0_525

; __device__ __forceinline__ void dil_issue(PP p, const DilUnit& q, DilRegs& R, int tid) {
;     ...
;     R.bias = -1.0e30f;
;     if (tid < 383) { const int sd = 255 - tid; if (sd >= 0 && sd <= 128) R.bias = p->in[2][t5_bucket(sd * q.d) * 8 + q.h] * 1.4426950408889634f; }
.LBB0_541:
	s_or_b64 exec, exec, s[16:17]
	s_load_dwordx2 s[16:17], s[28:29], 0x10
	v_lshl_add_u32 v52, v52, 3, s36
	v_ashrrev_i32_e32 v53, 31, v52
	s_waitcnt lgkmcnt(0)
	v_lshl_add_u64 v[52:53], v[52:53], 2, s[16:17]
	global_load_dword v219, v[52:53], off
	v_mov_b64_e32 v[52:53], s[34:35]

; __device__ __forceinline__ void attn_band64(const bf16_t* Ks, const bf16_t* Vt, const bf16x8 (&qf)[2], int a, int w, int quad, int fr,
;                                             const float* biasT, int kmin, f32x4 (&oacc)[4], float& mx_out, float& den_out) {
;     f32x4 s[10];
; #pragma unroll
;     for (int i = 0; i < 10; ++i) {
;         const int nt = (w + i) > 15 ? 15 : (w + i);
;         s[i] = (f32x4){0.f, 0.f, 0.f, 0.f};
; #pragma unroll
;         for (int ks = 0; ks < 2; ++ks) {
;             const bf16x8 kf = *(const bf16x8*)(Ks + (16 * nt + fr) * 72 + quad * 8 + 32 * ks);
;             s[i] = __builtin_amdgcn_mfma_f32_16x16x32_bf16(kf, qf[ks], s[i], 0, 0, 0);
;         }
;     }
;     float mx = -3.0e38f;
;     const float* tb = biasT + (127 - a + 4 * quad + 16 * w);
; #pragma unroll
;     for (int i = 0; i < 10; ++i) {
;         const bool dead = (kmin != 0) && ((w + i) < 8);
; #pragma unroll
;         for (int j = 0; j < 4; ++j) {
;             float v = s[i][j] * 0.18033688011112042f + tb[16 * i + j];
;             v = dead ? -1.0e30f : v;
;             s[i][j] = v; mx = fmaxf(mx, v);
;         }
;     }
.LBB0_543:
	s_and_b32 s2, s30, 7
	s_mulk_i32 s2, 0xc0
	s_ashr_i32 s3, s30, 3
	s_add_i32 s2, s2, s3
	s_ashr_i32 s16, s2, 31
	s_lshr_b32 s16, s16, 23
	s_add_i32 s16, s2, s16
	s_ashr_i32 s28, s16, 9
	s_and_b32 s16, s16, 0xfe00
	s_add_i32 s3, s2, 0x1ff
	s_and_b32 s17, s2, 0xfffffe00
	s_sub_i32 s2, s2, s16
	s_sext_i32_i16 s16, s2
	s_lshr_b32 s20, s16, 15
	s_bfe_u32 s16, s20, 0x4000c
	s_add_i32 s16, s2, s16
	s_bfe_u32 s21, s16, 0xc0004
	s_and_b32 s16, s16, 0xfff0
	s_sub_i32 s23, s2, s16
	s_bfe_i32 s16, s21, 0x80000
	s_bfe_u32 s16, s16, 0x3000c
	s_add_i32 s16, s21, s16
	s_bfe_u32 s20, s20, 0x70009
	s_and_b32 s16, s16, 0x1ff8
	s_add_i32 s20, s2, s20
	s_sext_i32_i8 s2, s23
	s_sub_i32 s16, s21, s16
	s_ashr_i32 s21, s2, 30
	s_or_b32 s21, s21, 1
	s_cmpk_eq_i32 s17, 0x200
	s_cselect_b32 s17, 4, 1
	s_cselect_b32 s22, 2, 4
	s_cmpk_lt_u32 s3, 0x3ff
	s_cselect_b32 s24, 16, s17
	v_cvt_f32_ubyte0_e32 v55, s24
	v_cvt_f32_i32_e32 v54, s2
	v_rcp_iflag_f32_e32 v56, v55
	s_cselect_b32 s17, 0, s22
	v_mul_f32_e32 v56, v54, v56
	v_trunc_f32_e32 v122, v56
	v_fma_f32 v54, -v122, v55, v54
	v_cmp_ge_f32_e64 s[2:3], |v54|, v55
	s_and_b64 s[2:3], s[2:3], exec
	s_mul_i32 s3, s14, 0x12000
	s_cselect_b32 s2, s21, 0
	s_add_i32 s22, s3, 0
	v_add_u32_e32 v134, s22, v71
	v_add_u32_e32 v94, v134, v72
	ds_read_b128 v[54:57], v94
	ds_read_b128 v[94:97], v94 offset:64
	v_add_u32_e32 v102, v134, v74
	s_waitcnt lgkmcnt(1)
	v_mfma_f32_16x16x32_bf16 v[54:57], v[54:57], v[2:5], 0
	ds_read_b128 v[98:101], v102
	v_add_u32_e32 v110, v134, v76
	v_add_u32_e32 v114, v134, v77
	s_waitcnt lgkmcnt(1)
	v_mfma_f32_16x16x32_bf16 v[54:57], v[94:97], v[6:9], v[54:57]
	ds_read_b128 v[94:97], v102 offset:64
	v_add_u32_e32 v102, v134, v75
	v_add_u32_e32 v118, v134, v78
	s_waitcnt lgkmcnt(1)
	v_mfma_f32_16x16x32_bf16 v[98:101], v[98:101], v[2:5], 0
	v_add_u32_e32 v123, v134, v79
	v_cvt_i32_f32_e32 v126, v122
	s_sext_i32_i16 s3, s20
	s_waitcnt lgkmcnt(0)
	v_mfma_f32_16x16x32_bf16 v[94:97], v[94:97], v[6:9], v[98:101]
	s_nop 2
	ds_read_b128 v[98:101], v102
	ds_read_b128 v[102:105], v102 offset:64
	ds_read_b128 v[106:109], v110
	v_readfirstlane_b32 s20, v126
	s_waitcnt lgkmcnt(2)
	v_mfma_f32_16x16x32_bf16 v[98:101], v[98:101], v[2:5], 0
	v_add_u32_e32 v126, v134, v80
	v_add_u32_e32 v130, v134, v81
	v_add_u32_e32 v134, v134, v82
	s_waitcnt lgkmcnt(1)
	v_mfma_f32_16x16x32_bf16 v[98:101], v[102:105], v[6:9], v[98:101]
	ds_read_b128 v[102:105], v110 offset:64
	ds_read_b128 v[110:113], v114
	s_add_i32 s2, s20, s2
	s_waitcnt lgkmcnt(2)
	v_mfma_f32_16x16x32_bf16 v[106:109], v[106:109], v[2:5], 0
	s_sext_i32_i8 s21, s2
	s_mul_i32 s2, s2, s24
	s_sub_i32 s20, s23, s2
	s_waitcnt lgkmcnt(1)
	v_mfma_f32_16x16x32_bf16 v[102:105], v[102:105], v[6:9], v[106:109]
	s_add_i32 s23, s22, 0x11600
	s_nop 1
	ds_read_b128 v[106:109], v114 offset:64
	ds_read_b128 v[114:117], v118
	s_waitcnt lgkmcnt(2)
	v_mfma_f32_16x16x32_bf16 v[110:113], v[110:113], v[2:5], 0
	s_lshl_b32 s3, s3, 4
	s_and_b32 s3, s3, 0xfffff800
	s_and_b32 s2, s20, 0xff
	s_waitcnt lgkmcnt(1)
	v_mfma_f32_16x16x32_bf16 v[106:109], v[106:109], v[6:9], v[110:113]
	s_add_i32 s21, s3, s21
	s_nop 1
	ds_read_b128 v[110:113], v118 offset:64
	ds_read_b128 v[118:121], v123
	s_waitcnt lgkmcnt(2)
	v_mfma_f32_16x16x32_bf16 v[114:117], v[114:117], v[2:5], 0
	s_cmp_eq_u32 s2, 0
	s_cselect_b64 s[2:3], -1, 0
	s_and_b64 vcc, s[42:43], s[2:3]
	s_waitcnt lgkmcnt(1)
	v_mfma_f32_16x16x32_bf16 v[110:113], v[110:113], v[6:9], v[114:117]
	s_ashr_i32 s29, s28, 31
	s_nop 1
	ds_read_b128 v[114:117], v126
	ds_read_b128 v[122:125], v123 offset:64
	ds_read_b128 v[126:129], v126 offset:64
	s_waitcnt lgkmcnt(3)
	v_mfma_f32_16x16x32_bf16 v[118:121], v[118:121], v[2:5], 0
	s_waitcnt lgkmcnt(1)
	v_mfma_f32_16x16x32_bf16 v[118:121], v[122:125], v[6:9], v[118:121]
	ds_read_b128 v[122:125], v130
	v_mfma_f32_16x16x32_bf16 v[114:117], v[114:117], v[2:5], 0
	s_waitcnt lgkmcnt(1)
	v_mfma_f32_16x16x32_bf16 v[114:117], v[126:129], v[6:9], v[114:117]
	ds_read_b128 v[126:129], v134
	ds_read_b128 v[130:133], v130 offset:64
	ds_read_b128 v[134:137], v134 offset:64
	s_waitcnt lgkmcnt(3)
	v_mfma_f32_16x16x32_bf16 v[122:125], v[122:125], v[2:5], 0
	s_waitcnt lgkmcnt(1)
	v_mfma_f32_16x16x32_bf16 v[122:125], v[130:133], v[6:9], v[122:125]
	v_lshlrev_b32_e32 v130, 2, v50
	v_add3_u32 v138, s23, v130, v92
	ds_read2_b32 v[130:131], v138 offset1:1
	v_mfma_f32_16x16x32_bf16 v[126:129], v[126:129], v[2:5], 0
	s_mov_b32 s23, 0xff61b1e6
	s_waitcnt lgkmcnt(0)
	v_fmamk_f32 v54, v54, 0x3e38aa3b, v130
	v_mfma_f32_16x16x32_bf16 v[126:129], v[134:137], v[6:9], v[126:129]
	ds_read2_b32 v[132:133], v138 offset0:2 offset1:3
	ds_read2_b32 v[134:135], v138 offset0:16 offset1:17
	ds_read2_b32 v[136:137], v138 offset0:18 offset1:19
	v_fmac_f32_e32 v131, 0x3e38aa3b, v55
	v_cndmask_b32_e32 v130, v54, v230, vcc
	v_cndmask_b32_e32 v131, v131, v230, vcc
	s_waitcnt lgkmcnt(2)
	v_fmamk_f32 v55, v56, 0x3e38aa3b, v132
	v_fmac_f32_e32 v133, 0x3e38aa3b, v57
	v_max3_f32 v54, v130, s23, v131
	v_cndmask_b32_e32 v132, v55, v230, vcc
	v_cndmask_b32_e32 v133, v133, v230, vcc
	s_waitcnt lgkmcnt(1)
	v_fmamk_f32 v55, v94, 0x3e38aa3b, v134
	s_and_b64 vcc, s[44:45], s[2:3]
	v_fmac_f32_e32 v135, 0x3e38aa3b, v95
	v_max3_f32 v54, v54, v132, v133
	v_cndmask_b32_e32 v134, v55, v230, vcc
	v_cndmask_b32_e32 v135, v135, v230, vcc
	v_max3_f32 v56, v54, v134, v135
	s_waitcnt lgkmcnt(0)
	v_fmamk_f32 v54, v96, 0x3e38aa3b, v136
	v_cndmask_b32_e32 v136, v54, v230, vcc
	ds_read2_b32 v[54:55], v138 offset0:32 offset1:33
	v_fmac_f32_e32 v137, 0x3e38aa3b, v97
	v_cndmask_b32_e32 v137, v137, v230, vcc
	v_max3_f32 v139, v56, v136, v137
	ds_read2_b32 v[56:57], v138 offset0:34 offset1:35
	ds_read2_b32 v[94:95], v138 offset0:48 offset1:49
	ds_read2_b32 v[96:97], v138 offset0:50 offset1:51
	s_waitcnt lgkmcnt(3)
; __device__ __forceinline__ void attn_band64(const bf16_t* Ks, const bf16_t* Vt, const bf16x8 (&qf)[2], int a, int w, int quad, int fr,
;                                             const float* biasT, int kmin, f32x4 (&oacc)[4], float& mx_out, float& den_out) {
;     ...
;     float mx = -3.0e38f;
;     const float* tb = biasT + (127 - a + 4 * quad + 16 * w);
; #pragma unroll
;     for (int i = 0; i < 10; ++i) {
;         const bool dead = (kmin != 0) && ((w + i) < 8);
; #pragma unroll
;         for (int j = 0; j < 4; ++j) {
;             float v = s[i][j] * 0.18033688011112042f + tb[16 * i + j];
;             v = dead ? -1.0e30f : v;
;             s[i][j] = v; mx = fmaxf(mx, v);
;         }
;     }
;     mx = fmaxf(mx, __shfl_xor(mx, 16)); mx = fmaxf(mx, __shfl_xor(mx, 32));
	v_fmamk_f32 v54, v98, 0x3e38aa3b, v54
	s_and_b64 vcc, s[46:47], s[2:3]
	v_fmac_f32_e32 v55, 0x3e38aa3b, v99
	v_cndmask_b32_e32 v98, v54, v230, vcc
	v_cndmask_b32_e32 v99, v55, v230, vcc
	s_waitcnt lgkmcnt(2)
	v_fmamk_f32 v55, v100, 0x3e38aa3b, v56
	v_fmac_f32_e32 v57, 0x3e38aa3b, v101
	v_max3_f32 v54, v139, v98, v99
	v_cndmask_b32_e32 v100, v55, v230, vcc
	v_cndmask_b32_e32 v101, v57, v230, vcc
	s_waitcnt lgkmcnt(1)
	v_fmamk_f32 v55, v102, 0x3e38aa3b, v94
	s_and_b64 vcc, s[48:49], s[2:3]
	v_fmac_f32_e32 v95, 0x3e38aa3b, v103
	v_max3_f32 v54, v54, v100, v101
	v_cndmask_b32_e32 v102, v55, v230, vcc
	v_cndmask_b32_e32 v103, v95, v230, vcc
	v_max3_f32 v56, v54, v102, v103
	s_waitcnt lgkmcnt(0)
	v_fmamk_f32 v54, v104, 0x3e38aa3b, v96
	v_cndmask_b32_e32 v104, v54, v230, vcc
	ds_read2_b32 v[54:55], v138 offset0:64 offset1:65
	v_fmac_f32_e32 v97, 0x3e38aa3b, v105
	v_cndmask_b32_e32 v105, v97, v230, vcc
	v_max3_f32 v139, v56, v104, v105
	ds_read2_b32 v[56:57], v138 offset0:66 offset1:67
	ds_read2_b32 v[94:95], v138 offset0:80 offset1:81
	ds_read2_b32 v[96:97], v138 offset0:82 offset1:83
	s_waitcnt lgkmcnt(3)
	v_fmamk_f32 v54, v106, 0x3e38aa3b, v54
	s_and_b64 vcc, s[50:51], s[2:3]
	v_fmac_f32_e32 v55, 0x3e38aa3b, v107
	v_cndmask_b32_e32 v106, v54, v230, vcc
	v_cndmask_b32_e32 v107, v55, v230, vcc
	s_waitcnt lgkmcnt(2)
	v_fmamk_f32 v55, v108, 0x3e38aa3b, v56
	v_fmac_f32_e32 v57, 0x3e38aa3b, v109
	v_max3_f32 v54, v139, v106, v107
	v_cndmask_b32_e32 v108, v55, v230, vcc
	v_cndmask_b32_e32 v109, v57, v230, vcc
	s_waitcnt lgkmcnt(1)
	v_fmamk_f32 v55, v110, 0x3e38aa3b, v94
	s_and_b64 vcc, s[52:53], s[2:3]
	v_fmac_f32_e32 v95, 0x3e38aa3b, v111
	v_max3_f32 v54, v54, v108, v109
	v_cndmask_b32_e32 v110, v55, v230, vcc
	v_cndmask_b32_e32 v111, v95, v230, vcc
	v_max3_f32 v56, v54, v110, v111
	s_waitcnt lgkmcnt(0)
	v_fmamk_f32 v54, v112, 0x3e38aa3b, v96
	v_cndmask_b32_e32 v112, v54, v230, vcc
	ds_read2_b32 v[54:55], v138 offset0:96 offset1:97
	v_fmac_f32_e32 v97, 0x3e38aa3b, v113
	v_cndmask_b32_e32 v113, v97, v230, vcc
	v_max3_f32 v139, v56, v112, v113
	ds_read2_b32 v[56:57], v138 offset0:98 offset1:99
	ds_read2_b32 v[94:95], v138 offset0:112 offset1:113
	ds_read2_b32 v[96:97], v138 offset0:114 offset1:115
	s_waitcnt lgkmcnt(3)
	v_fmamk_f32 v54, v118, 0x3e38aa3b, v54
	s_and_b64 vcc, s[54:55], s[2:3]
	v_fmac_f32_e32 v55, 0x3e38aa3b, v119
	v_cndmask_b32_e32 v118, v54, v230, vcc
	v_cndmask_b32_e32 v119, v55, v230, vcc
	s_waitcnt lgkmcnt(2)
	v_fmamk_f32 v55, v120, 0x3e38aa3b, v56
	v_fmac_f32_e32 v57, 0x3e38aa3b, v121
	v_max3_f32 v54, v139, v118, v119
	v_cndmask_b32_e32 v120, v55, v230, vcc
	v_cndmask_b32_e32 v121, v57, v230, vcc
	s_waitcnt lgkmcnt(1)
	v_fmamk_f32 v55, v114, 0x3e38aa3b, v94
	s_and_b64 vcc, s[56:57], s[2:3]
	v_fmac_f32_e32 v95, 0x3e38aa3b, v115
	v_max3_f32 v54, v54, v120, v121
	v_cndmask_b32_e32 v139, v55, v230, vcc
	v_cndmask_b32_e32 v140, v95, v230, vcc
	v_max3_f32 v56, v54, v139, v140
	s_waitcnt lgkmcnt(0)
	v_fmamk_f32 v54, v116, 0x3e38aa3b, v96
	v_cndmask_b32_e32 v116, v54, v230, vcc
	v_fmac_f32_e32 v97, 0x3e38aa3b, v117
	ds_read2_b32 v[54:55], v138 offset0:128 offset1:129
	v_cndmask_b32_e32 v141, v97, v230, vcc
	v_max3_f32 v114, v56, v116, v141
	ds_read2_b32 v[56:57], v138 offset0:130 offset1:131
	ds_read2_b32 v[94:95], v138 offset0:144 offset1:145
	ds_read2_b32 v[96:97], v138 offset0:146 offset1:147
	s_and_b64 vcc, s[58:59], s[2:3]
	s_waitcnt lgkmcnt(3)
	v_fmamk_f32 v54, v122, 0x3e38aa3b, v54
	v_fmac_f32_e32 v55, 0x3e38aa3b, v123
	s_waitcnt lgkmcnt(2)
	v_fmamk_f32 v56, v124, 0x3e38aa3b, v56
	v_fmac_f32_e32 v57, 0x3e38aa3b, v125
	v_cndmask_b32_e32 v138, v54, v230, vcc
	v_cndmask_b32_e32 v55, v55, v230, vcc
	v_cndmask_b32_e32 v56, v56, v230, vcc
	v_cndmask_b32_e32 v57, v57, v230, vcc
	s_waitcnt lgkmcnt(1)
	v_fmamk_f32 v94, v126, 0x3e38aa3b, v94
	s_and_b64 vcc, s[60:61], s[2:3]
	v_cndmask_b32_e32 v142, v94, v230, vcc
	s_waitcnt lgkmcnt(0)
	v_fmamk_f32 v94, v128, 0x3e38aa3b, v96
	v_and_b32_e32 v96, 64, v226
	v_max3_f32 v54, v114, v138, v55
	v_fmac_f32_e32 v95, 0x3e38aa3b, v127
	v_cndmask_b32_e32 v143, v94, v230, vcc
	v_fmac_f32_e32 v97, 0x3e38aa3b, v129
	v_xor_b32_e32 v94, 16, v226
	v_add_u32_e32 v96, 64, v96
	v_max3_f32 v54, v54, v56, v57
	v_cndmask_b32_e32 v95, v95, v230, vcc
	v_cndmask_b32_e32 v144, v97, v230, vcc
	v_cmp_lt_i32_e32 vcc, v94, v96
	v_max3_f32 v54, v54, v142, v95
	v_max3_f32 v54, v54, v143, v144
	v_cndmask_b32_e32 v94, v226, v94, vcc
	v_lshlrev_b32_e32 v145, 2, v94
	ds_bpermute_b32 v94, v145, v54
	s_sext_i32_i8 s2, s20
	s_waitcnt lgkmcnt(0)
	v_max_f32_e32 v94, v94, v94
	v_max_f32_e32 v54, v54, v94
	v_xor_b32_e32 v94, 32, v226
	v_cmp_lt_i32_e32 vcc, v94, v96
	s_nop 1
	v_cndmask_b32_e32 v94, v226, v94, vcc
	v_lshlrev_b32_e32 v146, 2, v94
	ds_bpermute_b32 v94, v146, v54
	s_waitcnt lgkmcnt(0)
; __device__ __forceinline__ unsigned pk2(float lo, float hi) { const hf32x2 v = {lo, hi}; return __builtin_bit_cast(unsigned, __builtin_convertvector(v, hbf16x2)); }
; __device__ __forceinline__ void attn_band64(const bf16_t* Ks, const bf16_t* Vt, const bf16x8 (&qf)[2], int a, int w, int quad, int fr,
;                                             const float* biasT, int kmin, f32x4 (&oacc)[4], float& mx_out, float& den_out) {
;     ...
;     float sum = 0.f;
; #pragma unroll
;     for (int i = 0; i < 10; ++i)
; #pragma unroll
;         for (int j = 0; j < 4; ++j) { const float pv = __builtin_amdgcn_exp2f(s[i][j] - mx); s[i][j] = pv; sum += pv; }
;     sum += __shfl_xor(sum, 16); sum += __shfl_xor(sum, 32);
; #pragma unroll
;     for (int dt = 0; dt < 4; ++dt) oacc[dt] = (f32x4){0.f, 0.f, 0.f, 0.f};
; #pragma unroll
;     for (int k2 = 0; k2 < 5; ++k2) {
;         u32x4 pp; pp.x = pk2(s[2 * k2][0], s[2 * k2][1]); pp.y = pk2(s[2 * k2][2], s[2 * k2][3]); pp.z = pk2(s[2 * k2 + 1][0], s[2 * k2 + 1][1]); pp.w = pk2(s[2 * k2 + 1][2], s[2 * k2 + 1][3]);
;         const bf16x8 pf = __builtin_bit_cast(bf16x8, pp);
;         const int t0 = w + 2 * k2, t1 = (t0 + 1) > 15 ? 15 : (t0 + 1);
; #pragma unroll
;         for (int dt = 0; dt < 4; ++dt) {
;             const bf16_t* vp = Vt + (16 * dt + fr) * VS + quad * 4;
;             const u32x2 lo = *(const u32x2*)(vp + 16 * t0), hi = *(const u32x2*)(vp + 16 * t1);
;             u32x4 vv; vv.x = lo.x; vv.y = lo.y; vv.z = hi.x; vv.w = hi.y;
;             oacc[dt] = __builtin_amdgcn_mfma_f32_16x16x32_bf16(__builtin_bit_cast(bf16x8, vv), pf, oacc[dt], 0, 0, 0);
;         }
;     }
	v_max_f32_e32 v94, v94, v94
	v_max_f32_e32 v94, v54, v94
	v_sub_f32_e32 v54, v130, v94
	v_exp_f32_e32 v96, v54
	v_sub_f32_e32 v54, v131, v94
	v_exp_f32_e32 v97, v54
	v_sub_f32_e32 v54, v132, v94
	v_exp_f32_e32 v114, v54
	v_sub_f32_e32 v54, v133, v94
	v_exp_f32_e32 v115, v54
	v_sub_f32_e32 v117, v134, v94
	v_add_f32_e32 v54, 0, v96
	v_exp_f32_e32 v117, v117
	v_sub_f32_e32 v122, v135, v94
	v_add_f32_e32 v54, v97, v54
	v_exp_f32_e32 v122, v122
	v_sub_f32_e32 v123, v136, v94
	v_add_f32_e32 v54, v114, v54
	v_exp_f32_e32 v123, v123
	v_sub_f32_e32 v124, v137, v94
	v_add_f32_e32 v54, v115, v54
	v_exp_f32_e32 v124, v124
	v_sub_f32_e32 v98, v98, v94
	v_add_f32_e32 v54, v117, v54
	v_exp_f32_e32 v125, v98
	v_sub_f32_e32 v98, v99, v94
	v_add_f32_e32 v54, v122, v54
	v_exp_f32_e32 v126, v98
	v_sub_f32_e32 v98, v100, v94
	v_add_f32_e32 v54, v123, v54
	v_exp_f32_e32 v127, v98
	v_sub_f32_e32 v98, v101, v94
	v_add_f32_e32 v54, v124, v54
	v_exp_f32_e32 v128, v98
	v_sub_f32_e32 v98, v102, v94
	v_add_f32_e32 v54, v125, v54
	v_exp_f32_e32 v129, v98
	v_sub_f32_e32 v98, v103, v94
	v_add_f32_e32 v54, v126, v54
	v_exp_f32_e32 v130, v98
	v_sub_f32_e32 v98, v104, v94
	v_add_f32_e32 v54, v127, v54
	v_exp_f32_e32 v131, v98
	v_sub_f32_e32 v98, v105, v94
	v_add_f32_e32 v54, v128, v54
	v_exp_f32_e32 v132, v98
	v_sub_f32_e32 v98, v106, v94
	v_add_f32_e32 v54, v129, v54
	v_exp_f32_e32 v133, v98
	v_sub_f32_e32 v98, v107, v94
	v_add_f32_e32 v54, v130, v54
	v_exp_f32_e32 v134, v98
	v_sub_f32_e32 v98, v108, v94
	v_add_f32_e32 v54, v131, v54
	v_exp_f32_e32 v135, v98
	v_sub_f32_e32 v98, v109, v94
	v_add_f32_e32 v54, v132, v54
	v_exp_f32_e32 v136, v98
	v_sub_f32_e32 v98, v110, v94
	v_add_f32_e32 v54, v133, v54
	v_exp_f32_e32 v137, v98
	v_sub_f32_e32 v98, v111, v94
	v_add_f32_e32 v54, v134, v54
	v_exp_f32_e32 v147, v98
	v_sub_f32_e32 v98, v112, v94
	v_add_f32_e32 v54, v135, v54
	v_exp_f32_e32 v148, v98
	v_sub_f32_e32 v98, v113, v94
	v_add_f32_e32 v54, v136, v54
	v_exp_f32_e32 v149, v98
	v_sub_f32_e32 v98, v118, v94
	v_add_f32_e32 v54, v137, v54
	v_exp_f32_e32 v150, v98
	v_sub_f32_e32 v98, v119, v94
	v_add_f32_e32 v54, v147, v54
	v_exp_f32_e32 v151, v98
	v_sub_f32_e32 v98, v120, v94
	v_add_f32_e32 v54, v148, v54
	v_exp_f32_e32 v152, v98
	v_sub_f32_e32 v98, v121, v94
	v_add_f32_e32 v54, v149, v54
	v_exp_f32_e32 v153, v98
	v_add_f32_e32 v54, v150, v54
	v_add_f32_e32 v54, v151, v54
	v_add_f32_e32 v54, v152, v54
	v_add_f32_e32 v118, v153, v54
	v_lshlrev_b32_e32 v54, 1, v50
	v_add3_u32 v154, s22, v54, v83
	v_cvt_pk_bf16_f32 v96, v96, v97
	v_cvt_pk_bf16_f32 v97, v114, v115
	v_lshl_add_u32 v110, v69, 1, v154
	v_lshl_add_u32 v114, v73, 1, v154
	ds_read_b64 v[100:101], v110 offset:36864
	ds_read_b64 v[102:103], v114 offset:36896
	v_cvt_pk_bf16_f32 v98, v117, v122
	v_sub_f32_e32 v117, v139, v94
	ds_read_b64 v[106:107], v114 offset:45472
	ds_read_b64 v[104:105], v110 offset:45440
	ds_read_b64 v[108:109], v110 offset:54016
	ds_read_b64 v[112:113], v110 offset:62592
	ds_read_b64 v[110:111], v114 offset:54048
	ds_read_b64 v[114:115], v114 offset:62624
	v_exp_f32_e32 v139, v117
	v_sub_f32_e32 v117, v140, v94
	v_exp_f32_e32 v140, v117
	v_sub_f32_e32 v116, v116, v94
	v_exp_f32_e32 v155, v116
	v_cvt_pk_bf16_f32 v99, v123, v124
	v_add_f32_e32 v116, v139, v118
	v_add_f32_e32 v116, v140, v116
	s_waitcnt lgkmcnt(6)
	v_mfma_f32_16x16x32_bf16 v[100:103], v[100:103], v[96:99], 0
	v_lshl_add_u32 v157, v85, 1, v154
	v_add_f32_e32 v156, v155, v116
	ds_read_b64 v[118:119], v157 offset:36896
	s_waitcnt lgkmcnt(5)
	v_mfma_f32_16x16x32_bf16 v[104:107], v[104:107], v[96:99], 0
	v_sub_f32_e32 v55, v55, v94
	v_exp_f32_e32 v55, v55
	v_sub_f32_e32 v56, v56, v94
	s_waitcnt lgkmcnt(2)
	v_mfma_f32_16x16x32_bf16 v[108:111], v[108:111], v[96:99], 0
	v_exp_f32_e32 v56, v56
	v_sub_f32_e32 v57, v57, v94
	v_exp_f32_e32 v57, v57
	s_waitcnt lgkmcnt(1)
	v_mfma_f32_16x16x32_bf16 v[96:99], v[112:115], v[96:99], 0
	v_cvt_pk_bf16_f32 v112, v125, v126
	v_lshl_add_u32 v126, v84, 1, v154
	ds_read_b64 v[116:117], v126 offset:36864
	v_cvt_pk_bf16_f32 v113, v127, v128
	v_cvt_pk_bf16_f32 v114, v129, v130
	v_cvt_pk_bf16_f32 v115, v131, v132
	ds_read_b64 v[122:123], v157 offset:45472
	ds_read_b64 v[120:121], v126 offset:45440
	ds_read_b64 v[124:125], v126 offset:54016
	ds_read_b64 v[128:129], v126 offset:62592
	ds_read_b64 v[126:127], v157 offset:54048
	ds_read_b64 v[130:131], v157 offset:62624
	s_waitcnt lgkmcnt(6)
	v_mfma_f32_16x16x32_bf16 v[100:103], v[116:119], v[112:115], v[100:103]
	v_sub_f32_e32 v116, v141, v94
	v_exp_f32_e32 v132, v116
	v_sub_f32_e32 v116, v138, v94
	v_exp_f32_e32 v138, v116
	s_waitcnt lgkmcnt(1)
	v_mfma_f32_16x16x32_bf16 v[108:111], v[124:127], v[112:115], v[108:111]
	v_add_f32_e32 v116, v132, v156
	v_lshl_add_u32 v126, v86, 1, v154
	v_add_f32_e32 v116, v138, v116
	s_waitcnt lgkmcnt(0)
	v_mfma_f32_16x16x32_bf16 v[96:99], v[128:131], v[112:115], v[96:99]
	v_lshl_add_u32 v130, v87, 1, v154
	v_add_f32_e32 v141, v55, v116
	ds_read_b64 v[116:117], v126 offset:36864
	ds_read_b64 v[118:119], v130 offset:36896
	v_mfma_f32_16x16x32_bf16 v[104:107], v[120:123], v[112:115], v[104:107]
	v_cvt_pk_bf16_f32 v112, v133, v134
	v_cvt_pk_bf16_f32 v113, v135, v136
	v_cvt_pk_bf16_f32 v114, v137, v147
	v_cvt_pk_bf16_f32 v115, v148, v149
	ds_read_b64 v[122:123], v130 offset:45472
	ds_read_b64 v[120:121], v126 offset:45440
	ds_read_b64 v[124:125], v126 offset:54016
	ds_read_b64 v[128:129], v126 offset:62592
	ds_read_b64 v[126:127], v130 offset:54048
	ds_read_b64 v[130:131], v130 offset:62624
	s_waitcnt lgkmcnt(6)
	v_mfma_f32_16x16x32_bf16 v[100:103], v[116:119], v[112:115], v[100:103]
	v_sub_f32_e32 v116, v142, v94
	v_exp_f32_e32 v133, v116
	v_add_f32_e32 v116, v56, v141
	s_waitcnt lgkmcnt(1)
; __device__ __forceinline__ unsigned pk2(float lo, float hi) { const hf32x2 v = {lo, hi}; return __builtin_bit_cast(unsigned, __builtin_convertvector(v, hbf16x2)); }
; __device__ __forceinline__ void attn_band64(const bf16_t* Ks, const bf16_t* Vt, const bf16x8 (&qf)[2], int a, int w, int quad, int fr,
;                                             const float* biasT, int kmin, f32x4 (&oacc)[4], float& mx_out, float& den_out) {
;     ...
;     for (int k2 = 0; k2 < 5; ++k2) {
;         u32x4 pp; pp.x = pk2(s[2 * k2][0], s[2 * k2][1]); pp.y = pk2(s[2 * k2][2], s[2 * k2][3]); pp.z = pk2(s[2 * k2 + 1][0], s[2 * k2 + 1][1]); pp.w = pk2(s[2 * k2 + 1][2], s[2 * k2 + 1][3]);
;         const bf16x8 pf = __builtin_bit_cast(bf16x8, pp);
;         const int t0 = w + 2 * k2, t1 = (t0 + 1) > 15 ? 15 : (t0 + 1);
; #pragma unroll
;         for (int dt = 0; dt < 4; ++dt) {
;             const bf16_t* vp = Vt + (16 * dt + fr) * VS + quad * 4;
;             const u32x2 lo = *(const u32x2*)(vp + 16 * t0), hi = *(const u32x2*)(vp + 16 * t1);
;             u32x4 vv; vv.x = lo.x; vv.y = lo.y; vv.z = hi.x; vv.w = hi.y;
;             oacc[dt] = __builtin_amdgcn_mfma_f32_16x16x32_bf16(__builtin_bit_cast(bf16x8, vv), pf, oacc[dt], 0, 0, 0);
;         }
;     }
; __device__ __forceinline__ void dil_compute(PP p, const DilUnit& q, const unsigned char* buf, int tid, const bf16x8 (&qf)[2]) {
;     ...
;     const float inv = 1.0f / den;
;     bf16_t* ob = (bf16_t*)(p->ws + WS_OB) + ((size_t)q.br * T + rowq) * 512 + q.h * 64 + quad * 4;
; #pragma unroll
;     for (int dt = 0; dt < 4; ++dt) { u32x2 o; o.x = pk2(oacc[dt][0] * inv, oacc[dt][1] * inv); o.y = pk2(oacc[dt][2] * inv, oacc[dt][3] * inv); *(u32x2*)(ob + 16 * dt) = o; }
;     if (quad == 0) ((float*)(p->ws + WS_LSE))[((size_t)q.br * T + rowq) * 8 + q.h] = mx * 0.6931471805599453f + __logf(den);
	v_mfma_f32_16x16x32_bf16 v[108:111], v[124:127], v[112:115], v[108:111]
	v_add_f32_e32 v116, v57, v116
	v_lshl_add_u32 v126, v88, 1, v154
	v_add_f32_e32 v134, v133, v116
	s_waitcnt lgkmcnt(0)
	v_mfma_f32_16x16x32_bf16 v[96:99], v[128:131], v[112:115], v[96:99]
	v_lshl_add_u32 v130, v89, 1, v154
	ds_read_b64 v[116:117], v126 offset:36864
	ds_read_b64 v[118:119], v130 offset:36896
	v_mfma_f32_16x16x32_bf16 v[104:107], v[120:123], v[112:115], v[104:107]
	v_cvt_pk_bf16_f32 v112, v150, v151
	v_cvt_pk_bf16_f32 v113, v152, v153
	v_cvt_pk_bf16_f32 v114, v139, v140
	v_cvt_pk_bf16_f32 v115, v155, v132
	v_sub_f32_e32 v95, v95, v94
	ds_read_b64 v[122:123], v130 offset:45472
	ds_read_b64 v[120:121], v126 offset:45440
	ds_read_b64 v[124:125], v126 offset:54016
	ds_read_b64 v[128:129], v126 offset:62592
	ds_read_b64 v[126:127], v130 offset:54048
	ds_read_b64 v[130:131], v130 offset:62624
	s_waitcnt lgkmcnt(6)
	v_mfma_f32_16x16x32_bf16 v[100:103], v[116:119], v[112:115], v[100:103]
	v_exp_f32_e32 v95, v95
	v_sub_f32_e32 v116, v143, v94
	s_sext_i32_i8 s22, s16
	s_waitcnt lgkmcnt(4)
	v_mfma_f32_16x16x32_bf16 v[104:107], v[120:123], v[112:115], v[104:107]
	v_exp_f32_e32 v120, v116
	v_sub_f32_e32 v116, v144, v94
	v_exp_f32_e32 v121, v116
	v_add_f32_e32 v116, v95, v134
	v_add_f32_e32 v116, v120, v116
	s_waitcnt lgkmcnt(1)
	v_mfma_f32_16x16x32_bf16 v[108:111], v[124:127], v[112:115], v[108:111]
	v_add_f32_e32 v132, v121, v116
	s_waitcnt lgkmcnt(0)
	v_mfma_f32_16x16x32_bf16 v[96:99], v[128:131], v[112:115], v[96:99]
	v_cvt_pk_bf16_f32 v112, v138, v55
	v_cvt_pk_bf16_f32 v113, v56, v57
	v_lshl_add_u32 v55, v90, 1, v154
	v_lshl_add_u32 v56, v91, 1, v154
	ds_read_b64 v[116:117], v55 offset:36864
	ds_read_b64 v[118:119], v56 offset:36896
	v_cvt_pk_bf16_f32 v115, v120, v121
	ds_read_b64 v[120:121], v55 offset:45440
	ds_read_b64 v[124:125], v55 offset:54016
	ds_read_b64 v[128:129], v55 offset:62592
	ds_read_b64 v[122:123], v56 offset:45472
	ds_read_b64 v[126:127], v56 offset:54048
	ds_read_b64 v[130:131], v56 offset:62624
	ds_bpermute_b32 v55, v145, v132
	v_cvt_pk_bf16_f32 v114, v133, v95
	v_lshl_add_u32 v57, s2, 7, v70
	v_lshlrev_b32_e32 v57, s17, v57
	s_waitcnt lgkmcnt(7)
	v_mfma_f32_16x16x32_bf16 v[100:103], v[116:119], v[112:115], v[100:103]
	s_waitcnt lgkmcnt(0)
	v_add_f32_e32 v55, v132, v55
	ds_bpermute_b32 v56, v146, v55
	s_waitcnt lgkmcnt(0)
	v_add_f32_e32 v95, v55, v56
	v_div_scale_f32 v55, s[2:3], v95, v95, 1.0
	v_rcp_f32_e32 v116, v55
	v_mfma_f32_16x16x32_bf16 v[104:107], v[120:123], v[112:115], v[104:107]
	v_add_u32_e32 v56, s21, v57
	v_ashrrev_i32_e32 v57, 31, v56
	s_lshl_b64 s[2:3], s[28:29], 23
	v_mfma_f32_16x16x32_bf16 v[108:111], v[124:127], v[112:115], v[108:111]
	v_mfma_f32_16x16x32_bf16 v[96:99], v[128:131], v[112:115], v[96:99]
	v_fma_f32 v112, -v55, v116, 1.0
	v_fmac_f32_e32 v116, v112, v116
	v_div_scale_f32 v112, vcc, 1.0, v95, 1.0
	v_mul_f32_e32 v113, v112, v116
	v_fma_f32 v114, -v55, v113, v112
	v_fmac_f32_e32 v113, v114, v116
	v_fma_f32 v55, -v55, v113, v112
	v_div_fmas_f32 v55, v55, v116, v113
	v_lshl_add_u64 v[114:115], v[52:53], 0, s[2:3]
	v_lshlrev_b64 v[116:117], 10, v[56:57]
	s_lshl_b32 s2, s22, 6
	v_lshl_add_u64 v[114:115], v[114:115], 0, v[116:117]
	s_ashr_i32 s3, s2, 31
	v_div_fixup_f32 v112, v55, v95, 1.0
	v_lshl_add_u64 v[114:115], s[2:3], 1, v[114:115]
	v_mov_b32_e32 v55, v1
	v_lshl_add_u64 v[54:55], v[114:115], 0, v[54:55]
	s_mov_b64 s[2:3], 0x24600000
	v_lshl_add_u64 v[114:115], v[54:55], 0, s[2:3]
	s_mov_b32 s2, 0x24600000
	v_pk_mul_f32 v[100:101], v[100:101], v[112:113] op_sel_hi:[1,0]
	v_pk_mul_f32 v[102:103], v[102:103], v[112:113] op_sel_hi:[1,0]
	v_add_co_u32_e32 v54, vcc, s2, v54
	v_cvt_pk_bf16_f32 v100, v100, v101
	v_cvt_pk_bf16_f32 v101, v102, v103
	v_addc_co_u32_e32 v55, vcc, 0, v55, vcc
	global_store_dwordx2 v[54:55], v[100:101], off
	v_pk_mul_f32 v[54:55], v[104:105], v[112:113] op_sel_hi:[1,0]
	v_pk_mul_f32 v[100:101], v[106:107], v[112:113] op_sel_hi:[1,0]
	v_cvt_pk_bf16_f32 v54, v54, v55
	v_cvt_pk_bf16_f32 v55, v100, v101
	global_store_dwordx2 v[114:115], v[54:55], off offset:32
	v_pk_mul_f32 v[54:55], v[108:109], v[112:113] op_sel_hi:[1,0]
	v_pk_mul_f32 v[100:101], v[110:111], v[112:113] op_sel_hi:[1,0]
	v_cvt_pk_bf16_f32 v54, v54, v55
	v_cvt_pk_bf16_f32 v55, v100, v101
	global_store_dwordx2 v[114:115], v[54:55], off offset:64
	v_pk_mul_f32 v[54:55], v[96:97], v[112:113] op_sel_hi:[1,0]
	v_pk_mul_f32 v[96:97], v[98:99], v[112:113] op_sel_hi:[1,0]
	v_cvt_pk_bf16_f32 v54, v54, v55
	v_cvt_pk_bf16_f32 v55, v96, v97
	global_store_dwordx2 v[114:115], v[54:55], off offset:96
	s_and_saveexec_b64 s[2:3], s[62:63]
	s_cbranch_execz .LBB0_545
	s_mov_b32 s17, 0x800000
	v_cmp_gt_f32_e32 vcc, s17, v95
	s_mov_b32 s17, 0x3f317217
	v_mov_b32_e32 v55, 0x41b17218
	v_cndmask_b32_e64 v54, 0, 32, vcc
	v_ldexp_f32 v54, v95, v54
	v_log_f32_e32 v54, v54
	v_cndmask_b32_e32 v55, 0, v55, vcc
	v_lshlrev_b64 v[56:57], 5, v[56:57]
	v_mul_f32_e32 v95, 0x3f317217, v54
	v_fma_f32 v95, v54, s17, -v95
	v_fmac_f32_e32 v95, 0x3377d1cf, v54
	s_mov_b32 s17, 0x7f800000
	v_fmac_f32_e32 v95, 0x3f317217, v54
	v_cmp_lt_f32_e64 vcc, |v54|, s17
	s_nop 1
	v_cndmask_b32_e32 v54, v54, v95, vcc
	v_sub_f32_e32 v95, v54, v55
	v_mov_b32_e32 v54, s16
	s_lshl_b64 s[16:17], s[28:29], 18
	v_bfe_i32 v54, v54, 0, 8
	v_lshl_add_u64 v[52:53], v[52:53], 0, s[16:17]
	v_ashrrev_i32_e32 v55, 31, v54
	v_lshl_add_u64 v[52:53], v[52:53], 0, v[56:57]
	v_lshl_add_u64 v[52:53], v[54:55], 2, v[52:53]
	v_add_co_u32_e32 v52, vcc, 0x25e00000, v52
	v_fmac_f32_e32 v95, 0x3f317218, v94
	s_nop 0
	v_addc_co_u32_e32 v53, vcc, 0, v53, vcc
	global_store_dword v[52:53], v95, off
; __device__ __forceinline__ void dil_stage(const DilRegs& R, unsigned char* buf, int tid) {
;     bf16_t* Ks = (bf16_t*)(buf + DA_KS); bf16_t* Vt = (bf16_t*)(buf + DA_VT); float* biasT = (float*)(buf + DA_BIAS);
; #pragma unroll
;     for (int i = 0; i < 4; ++i) { const int bi = 2 * (tid >> 3) + (i & 1) + 128 * (i >> 1), ch = tid & 7; *(u32x4*)(Ks + bi * 72 + ch * 8) = R.kv[i]; }
; #pragma unroll
;     for (int i = 0; i < 4; i += 2) { const int bi = 2 * (tid >> 3) + 128 * (i >> 1), ch = tid & 7; vt_store_pair(Vt, ch * 8, bi, R.vv[i], R.vv[i + 1]); }
;     if (tid < 383) biasT[tid] = R.bias;
; }
; __device__ __forceinline__ void dil_attn_units(unsigned char* shm, int first, int stride) {
;     ...
;         if (more) { dil_stage(R, shm + (par ^ 1) * DA_BUF, tid); qcur[0] = R.qf[0]; qcur[1] = R.qf[1]; }
.LBB0_545:
	s_or_b64 exec, exec, s[2:3]
	s_andn2_b64 vcc, exec, s[12:13]
	s_xor_b32 s14, s14, 1
	s_cbranch_vccnz .LBB0_524
	s_waitcnt vmcnt(4)
	s_mul_i32 s2, s14, 0x12000
	s_add_i32 s12, s2, 0
	v_lshl_add_u32 v2, v60, 1, s12
	v_lshl_add_u32 v3, v65, 1, v2
	v_lshl_add_u32 v4, v66, 1, v2
	ds_write_b128 v3, v[10:13]
	ds_write_b128 v4, v[22:25]
	ds_write_b128 v3, v[30:33] offset:18432
	ds_write_b128 v4, v[34:37] offset:18432
	v_lshlrev_b32_e32 v3, 16, v26
	s_mov_b32 s2, 0xffff
	v_lshlrev_b32_e32 v53, 16, v38
	v_add3_u32 v2, v2, v67, v68
	v_and_or_b32 v3, v14, s2, v3
	v_and_or_b32 v53, v18, s2, v53
	v_lshrrev_b32_e32 v4, 16, v14
	ds_write2st64_b32 v2, v3, v53 offset0:144 offset1:145
	v_lshrrev_b32_e32 v3, 16, v18
	v_and_or_b32 v4, v26, s10, v4
	v_and_or_b32 v3, v38, s10, v3
	v_add_u32_e32 v53, 24, v2
	v_lshlrev_b32_e32 v5, 16, v27
	ds_write2st64_b32 v53, v4, v3 offset0:146 offset1:147
	v_lshlrev_b32_e32 v3, 16, v39
	v_and_or_b32 v5, v15, s2, v5
	v_and_or_b32 v3, v19, s2, v3
	v_add_u32_e32 v4, 48, v2
	v_lshrrev_b32_e32 v6, 16, v15
	ds_write2st64_b32 v4, v5, v3 offset0:148 offset1:149
	v_lshrrev_b32_e32 v3, 16, v19
	v_and_or_b32 v6, v27, s10, v6
	v_and_or_b32 v3, v39, s10, v3
	v_add_u32_e32 v4, 0x48, v2
	v_lshlrev_b32_e32 v7, 16, v28
	ds_write2st64_b32 v4, v6, v3 offset0:150 offset1:151
	v_lshlrev_b32_e32 v3, 16, v40
	v_and_or_b32 v7, v16, s2, v7
	v_and_or_b32 v3, v20, s2, v3
	v_add_u32_e32 v4, 0x60, v2
	v_lshrrev_b32_e32 v8, 16, v16
	ds_write2st64_b32 v4, v7, v3 offset0:152 offset1:153
	v_lshrrev_b32_e32 v3, 16, v20
	v_and_or_b32 v8, v28, s10, v8
	v_and_or_b32 v3, v40, s10, v3
	v_add_u32_e32 v4, 0x78, v2
	v_lshlrev_b32_e32 v9, 16, v29
	ds_write2st64_b32 v4, v8, v3 offset0:154 offset1:155
	v_lshlrev_b32_e32 v3, 16, v41
	v_and_or_b32 v9, v17, s2, v9
	v_and_or_b32 v3, v21, s2, v3
	v_add_u32_e32 v4, 0x90, v2
	v_lshrrev_b32_e32 v52, 16, v17
	ds_write2st64_b32 v4, v9, v3 offset0:156 offset1:157
	v_lshrrev_b32_e32 v3, 16, v21
	v_and_or_b32 v52, v29, s10, v52
	v_and_or_b32 v3, v41, s10, v3
	v_add_u32_e32 v2, 0xa8, v2
	ds_write2st64_b32 v2, v52, v3 offset0:158 offset1:159
	v_mul_f32_e32 v219, 0x3fb8aa3b, v219
	v_cndmask_b32_e64 v93, v93, v219, s[38:39]
	s_and_saveexec_b64 s[2:3], s[40:41]
	s_cbranch_execz .LBB0_523
	v_lshl_add_u32 v2, v51, 2, s12
	v_add_u32_e32 v2, 0x11600, v2
	ds_write_b32 v2, v93
	s_branch .LBB0_523
